# layer-1 input-projection GEMM: the 128 Z-column tiles of the 4th (half-empty) round are computed by the otherwise idle weight-conversion workgroups during the DeltaNet scan phase
# speedup vs baseline: 1.1439x; 1.0126x over previous
; #define LAS __attribute__((address_space(3)))
; __global__ void __launch_bounds__(512, 2) mk_fwd(Args a) {
;     extern __shared__ __attribute__((aligned(16))) unsigned char shm[];
;     LAS unsigned char* lds = (LAS unsigned char*)shm;
;     ...
;     run_phase(a.ph_lo, lds);
;     ...
;     cg::grid_group grid = cg::this_grid();
;     volatile LAS unsigned* st = (volatile LAS unsigned*)(lds + 131072);
;     if (threadIdx.x == 0) { st[0] = 0u; st[1] = 0u; }
;     __syncthreads();
_Z6mk_fwd4Args:
	s_mov_b32 s19, s2
	s_mov_b32 s100, 0
	s_load_dwordx4 s[20:23], s[0:1], 0x88
	s_load_dwordx2 s[2:3], s[0:1], 0x98
	s_add_u32 s4, s0, 0x98
	v_and_b32_e32 v201, 0x3ff, v0
	s_waitcnt lgkmcnt(0)
	v_writelane_b32 v253, s2, 0
	s_nop 1
	v_writelane_b32 v253, s3, 1
	v_writelane_b32 v253, s0, 2
	s_addc_u32 s5, s1, 0
	v_cmp_eq_u32_e64 s[2:3], 0, v201
	v_writelane_b32 v253, s1, 3
	s_mov_b64 s[0:1], exec
	v_writelane_b32 v253, s2, 4
	s_nop 1
	v_writelane_b32 v253, s3, 5
	s_and_b64 s[2:3], s[0:1], s[2:3]
	s_mov_b64 exec, s[2:3]
	s_cbranch_execz .LBB0_2
	s_add_i32 s2, 0, 0x20000
	v_mov_b32_e32 v1, 0
	v_mov_b32_e32 v2, s2
	s_add_i32 s2, 0, 0x20004
	ds_write_b32 v2, v1
	v_mov_b32_e32 v2, s2
	ds_write_b32 v2, v1

; __global__ void __launch_bounds__(512, 2) mk_fwd(Args a) {
;     ...
;     for (int ph = a.ph_lo; ph < a.ph_hi; ++ph) {
;         if (ph == PH_PER_LAYER || ph == 2 * PH_PER_LAYER - 1) continue;
;         run_phase(ph, lds);
;         if (ph + 1 < a.ph_hi) xcd_barrier(xb);
.LBB0_21:
	s_mov_b32 s100, 0
	s_add_i32 s22, s22, 1
	s_cmp_ge_i32 s22, s23
	s_cbranch_scc0 .LBB0_22
	s_getpc_b64 s[98:99]

; __global__ void __launch_bounds__(512, 2) mk_fwd(Args a) {
;     ...
;     for (int ph = a.ph_lo; ph < a.ph_hi; ++ph) {
;         if (ph == PH_PER_LAYER || ph == 2 * PH_PER_LAYER - 1) continue;
;         run_phase(ph, lds);
;         if (ph + 1 < a.ph_hi) xcd_barrier(xb);
.LBB0_29:
	s_cmp_eq_u32 s100, 1
	s_cbranch_scc0 .Lnorm29
	s_mov_b32 s100, 2
	s_branch .LBB0_22

; __device__ __forceinline__ void run_phase(int ph, LAS unsigned char* lds) {
;     ...
;     const int l = ph / PH_PER_LAYER, p = ph % PH_PER_LAYER;
;     float* stats = (float*)(ws + OFF_STATS);
;     const float* mur = (const float*)(ws + OFF_MUR);
;     const float* mu_in = l > 0 ? mur + (size_t)((l - 1) * 3 + 2) * T_ * 2 : nullptr;
;     const float* mu0 = mur + (size_t)(l * 3 + 0) * T_ * 2; const float* mu1 = mur + (size_t)(l * 3 + 1) * T_ * 2;
;     float* st0 = stats + (size_t)(l * 3 + 0) * T_ * 32; float* st1 = stats + (size_t)(l * 3 + 1) * T_ * 32; float* st2 = stats + (size_t)(l * 3 + 2) * T_ * 32;
;     const float* ln_g = a.in[5]; const float* ln_b = a.in[6];
;     pg8::StaticOrder S;
;     switch (p) {
;     case 0: if (PH_ENABLED(0)) { if (l == 0) pro_part(a, tb, 0, 0, tb.bid, tb.G, lds); } break;
;     case 1: if (PH_ENABLED(1)) { pg8::Gemm g{(const bf16_t*)(ws + OFF_YB), (const bf16_t*)(ws + OFF_WGU0), T_, 2 * FF_, D_}; S.init(g.M, g.N, tb.G, tb.bid);
;         EpiGU E{(bf16_t*)(ws + OFF_H), mu_in, (const float*)(ws + OFF_C12GU0), (const float*)(ws + OFF_C12GU0) + 5632}; pg8::gemm_phase(tb, lds, g, S, E); } break;
;     case 2: if (PH_ENABLED(2)) { pg8::Gemm g{(const bf16_t*)(ws + OFF_H), (const bf16_t*)(ws + OFF_WDN0), T_, D_, FF_}; S.init(g.M, g.N, tb.G, tb.bid);
;         EpiRes E{nullptr, (bf16_t*)(ws + OFF_YB), mu_in, l > 0 ? ln_g + ((l - 1) * 3 + 2) * D_ : nullptr, l > 0 ? ln_b + ((l - 1) * 3 + 2) * D_ : nullptr, st0, 0.5f}; pg8::gemm_phase(tb, lds, g, S, E); } break;
;     case 3: if (PH_ENABLED(3)) phase_statsfin(a, tb, l * 3 + 0); break;
;     case 4: if (PH_ENABLED(4)) { pg8::Gemm g{(const bf16_t*)(ws + OFF_YB), (const bf16_t*)(ws + OFF_WIN), T_, NING_, D_}; S.init(g.M, g.N, tb.G, tb.bid);
;         EpiIn E{mu0, (const float*)(ws + OFF_C12IN), (const float*)(ws + OFF_C12IN) + 3584, (bf16_t*)(ws + OFF_QK), (bf16_t*)(ws + OFF_VT), (bf16_t*)(ws + OFF_PC), (bf16_t*)(ws + OFF_Z)}; pg8::gemm_phase(tb, lds, g, S, E);
;         } break;
;     case 5: if (PH_ENABLED(5)) { phase_gates(a, tb, l); phase_attn(a, tb, l, lds); } break;
;     case 6: if (PH_ENABLED(6)) phase_dnprep(a, tb, l, lds); break;
;     case 7: if (PH_ENABLED(7)) { phase_dnscan(a, tb, lds);
;         if (tb.bid >= 128) { pro_part(a, tb, l, 1, tb.bid - 128, tb.G - 128, lds); if (l == 0) pro_part(a, tb, 1, 0, tb.bid - 128, tb.G - 128, lds); } } break;
.LBB0_30:
	s_mul_hi_i32 s2, s22, 0x92492493
	s_add_i32 s2, s2, s22
	s_lshr_b32 s3, s2, 31
	s_ashr_i32 s2, s2, 3
	s_add_i32 s50, s2, s3
	s_mul_i32 s2, s50, 14
	s_mov_b64 s[6:7], s[22:23]
	s_sub_i32 s8, s22, s2
	s_movk_i32 s101, 0x37f
	s_cmpk_lg_u32 s56, 0x100
	s_cbranch_scc1 .Lsf_nohook
	s_cmp_eq_u32 s8, 3
	s_cbranch_scc1 .Lsf_hook
	s_cmp_eq_u32 s8, 10
	s_cbranch_scc1 .Lsf_hook
	s_cmp_eq_u32 s8, 13
	s_cbranch_scc1 .Lsf_hook
	s_cmp_lg_u32 s50, 1
	s_cbranch_scc1 .Lsf_nohook
	s_cmp_lg_u32 s100, 0
	s_cbranch_scc1 .Lsf_nohook
	s_cmp_eq_u32 s8, 4
	s_cbranch_scc0 .Lin_chk7
	s_movk_i32 s101, 0x2ff
	s_branch .Lsf_nohook
.Lin_chk7:
	s_cmp_eq_u32 s8, 7
	s_cbranch_scc0 .Lsf_nohook
	s_cmpk_lt_u32 s19, 0x80
	s_cbranch_scc1 .Lsf_nohook
	s_mov_b32 s100, 1
	s_mov_b32 s8, 4
	s_add_i32 s68, s19, 0x280

;     __device__ bool next(int i, Unit& u) const {
;         const long L = (long)i * G + c; if (L >= nwg) return false;
;         int wgid = (int)L; { const int q = nwg / NXCD, r = nwg % NXCD, xcd = wgid % NXCD, off = wgid / NXCD; wgid = (xcd < r ? xcd * (q + 1) : r * (q + 1) + (xcd - r) * q) + off; }
;         const int nig = WGM * nN, gid = wgid / nig, fm = gid * WGM, gsz = (nM - fm) < WGM ? (nM - fm) : WGM;
;         u.pm = fm + ((wgid % nig) % gsz); u.pn = (wgid % nig) / gsz; return true;
.LBB0_1265:
	s_add_i32 s50, s50, 1
	s_mul_i32 s2, s50, s48
	s_mul_hi_u32 s3, s50, s56
	s_add_i32 s3, s3, s2
	s_mul_i32 s2, s50, s56
	s_add_u32 s14, s2, s68
	s_addc_u32 s15, s3, s49
	s_cmp_gt_i32 s14, s101
	s_cselect_b64 s[2:3], -1, 0
	s_and_b64 vcc, exec, s[2:3]
	s_cbranch_vccnz .LBB0_1267
	s_ashr_i32 s5, s14, 31
	s_lshr_b32 s5, s5, 29
	s_add_i32 s5, s14, s5
	s_ashr_i32 s10, s5, 3
	s_and_b32 s5, s5, -8
	s_sub_i32 s5, s14, s5
	s_cmp_lt_i32 s5, 0
	s_movk_i32 s11, 0x71
	s_cselect_b32 s11, s11, 0x70
	s_mul_i32 s5, s11, s5
	s_add_i32 s5, s5, s10
	s_mul_hi_i32 s10, s5, 0x92492493
	s_add_i32 s10, s10, s5
	s_lshr_b32 s11, s10, 31
	s_ashr_i32 s10, s10, 6
	s_add_i32 s10, s10, s11
	s_lshl_b32 s11, s10, 3
	s_sub_i32 s12, 64, s11
	s_min_i32 s12, s12, 8
	s_abs_i32 s13, s12
	v_cvt_f32_u32_e32 v0, s13
	s_sub_i32 s17, 0, s13
	s_mulk_i32 s10, 0x70
	s_sub_i32 s5, s5, s10
	v_rcp_iflag_f32_e32 v0, v0
	s_abs_i32 s10, s5
	s_xor_b32 s16, s5, s12
	s_ashr_i32 s16, s16, 31
	v_mul_f32_e32 v0, 0x4f7ffffe, v0
	v_cvt_u32_f32_e32 v0, v0
	s_nop 0
	v_readfirstlane_b32 s22, v0
	s_mul_i32 s17, s17, s22
	s_mul_hi_u32 s17, s22, s17
	s_add_i32 s22, s22, s17
	s_mul_hi_u32 s17, s10, s22
	s_mul_i32 s22, s17, s13
	s_sub_i32 s10, s10, s22
	s_add_i32 s23, s17, 1
	s_sub_i32 s22, s10, s13
	s_cmp_ge_u32 s10, s13
	s_cselect_b32 s17, s23, s17
	s_cselect_b32 s10, s22, s10
	s_add_i32 s22, s17, 1
	s_cmp_ge_u32 s10, s13
	s_cselect_b32 s10, s22, s17
	s_xor_b32 s10, s10, s16
	s_sub_i32 s10, s10, s16
	s_mul_i32 s12, s10, s12
	s_sub_i32 s5, s5, s12
	s_add_i32 s12, s5, s11

; #define LAS __attribute__((address_space(3)))
; __global__ void __launch_bounds__(512, 2) mk_fwd(Args a) {
;     extern __shared__ __attribute__((aligned(16))) unsigned char shm[];
;     LAS unsigned char* lds = (LAS unsigned char*)shm;
	.amdhsa_kernel _Z6mk_fwd4Args
		.amdhsa_group_segment_fixed_size 0
		.amdhsa_private_segment_fixed_size 0
		.amdhsa_kernarg_size 408
		.amdhsa_user_sgpr_count 2
		.amdhsa_user_sgpr_dispatch_ptr 0
		.amdhsa_user_sgpr_queue_ptr 0
		.amdhsa_user_sgpr_kernarg_segment_ptr 1
		.amdhsa_user_sgpr_dispatch_id 0
		.amdhsa_user_sgpr_kernarg_preload_length 0
		.amdhsa_user_sgpr_kernarg_preload_offset 0
		.amdhsa_user_sgpr_private_segment_size 0
		.amdhsa_uses_dynamic_stack 0
		.amdhsa_enable_private_segment 0
		.amdhsa_system_sgpr_workgroup_id_x 1
		.amdhsa_system_sgpr_workgroup_id_y 0
		.amdhsa_system_sgpr_workgroup_id_z 0
		.amdhsa_system_sgpr_workgroup_info 0
		.amdhsa_system_vgpr_workitem_id 2
		.amdhsa_next_free_vgpr 256
		.amdhsa_next_free_sgpr 102
		.amdhsa_accum_offset 256
		.amdhsa_reserve_vcc 1
		.amdhsa_float_round_mode_32 0
		.amdhsa_float_round_mode_16_64 0
		.amdhsa_float_denorm_mode_32 3
		.amdhsa_float_denorm_mode_16_64 3
		.amdhsa_dx10_clamp 1
		.amdhsa_ieee_mode 1
		.amdhsa_fp16_overflow 0
		.amdhsa_tg_split 0
		.amdhsa_exception_fp_ieee_invalid_op 0
		.amdhsa_exception_fp_denorm_src 0
		.amdhsa_exception_fp_ieee_div_zero 0
		.amdhsa_exception_fp_ieee_overflow 0
		.amdhsa_exception_fp_ieee_underflow 0
		.amdhsa_exception_fp_ieee_inexact 0
		.amdhsa_exception_int_div_zero 0
	.end_amdhsa_kernel

; #define LAS __attribute__((address_space(3)))
; __global__ void __launch_bounds__(512, 2) mk_fwd(Args a) {
;     extern __shared__ __attribute__((aligned(16))) unsigned char shm[];
;     LAS unsigned char* lds = (LAS unsigned char*)shm;
amdhsa.kernels:
  - .agpr_count:     0
    .args:
      - .offset:         0
        .size:           152
        .value_kind:     by_value
      - .offset:         152
        .size:           4
        .value_kind:     hidden_block_count_x
      - .offset:         156
        .size:           4
        .value_kind:     hidden_block_count_y
      - .offset:         160
        .size:           4
        .value_kind:     hidden_block_count_z
      - .offset:         164
        .size:           2
        .value_kind:     hidden_group_size_x
      - .offset:         166
        .size:           2
        .value_kind:     hidden_group_size_y
      - .offset:         168
        .size:           2
        .value_kind:     hidden_group_size_z
      - .offset:         170
        .size:           2
        .value_kind:     hidden_remainder_x
      - .offset:         172
        .size:           2
        .value_kind:     hidden_remainder_y
      - .offset:         174
        .size:           2
        .value_kind:     hidden_remainder_z
      - .offset:         192
        .size:           8
        .value_kind:     hidden_global_offset_x
      - .offset:         200
        .size:           8
        .value_kind:     hidden_global_offset_y
      - .offset:         208
        .size:           8
        .value_kind:     hidden_global_offset_z
      - .offset:         216
        .size:           2
        .value_kind:     hidden_grid_dims
      - .offset:         240
        .size:           8
        .value_kind:     hidden_multigrid_sync_arg
      - .offset:         272
        .size:           4
        .value_kind:     hidden_dynamic_lds_size
    .group_segment_fixed_size: 0
    .kernarg_segment_align: 8
    .kernarg_segment_size: 408
    .language:       OpenCL C
    .language_version:
      - 2
      - 0
    .max_flat_workgroup_size: 512
    .name:           _Z6mk_fwd4Args
    .private_segment_fixed_size: 0
    .sgpr_count:     108
    .sgpr_spill_count: 199
    .symbol:         _Z6mk_fwd4Args.kd
    .uniform_work_group_size: 1
    .uses_dynamic_stack: false
    .vgpr_count:     256
    .vgpr_spill_count: 0
    .wavefront_size: 64
